# down-proj epilogue: second column-half x1b load issued together with the first (spare quad + copy)
# baseline (speedup 1.0000x reference)
; __device__ __forceinline__ unsigned cvt_pk_bf16(float lo, float hi) { unsigned r; asm volatile("v_cvt_pk_bf16_f32 %0, %1, %2" : "=v"(r) : "v"(lo), "v"(hi)); return r; }
;     __device__ __forceinline__ void operator()(const f32x4 (&acc)[2][2][4][2], const Unit& u, int wr, int wc, int fr, int fq) const {
;         const int row0 = row_base + u.pm * BM + wr * 64 + fr, col0 = u.pn * BM + wc * 32 + 8 * fq;
; #pragma unroll
;         for (int ai = 0; ai < 2; ++ai)
; #pragma unroll
;             for (int m = 0; m < 4; ++m) { const int row = row0 + ai * HALF + m * 16; bf16_t* rp = xb + (size_t)row * 2048 + col0; float s = 0.f;
; #pragma unroll
;                 for (int bj = 0; bj < 2; ++bj) { const u32x4 x = *(const u32x4*)(rp + bj * HALF); float v[8];
; #pragma unroll
;                     for (int e = 0; e < 4; ++e) { v[2 * e] = __builtin_bit_cast(float, x[e] << 16) + acc[ai][bj][m][e >> 1][(2 * e) & 3]; v[2 * e + 1] = __builtin_bit_cast(float, x[e] & 0xffff0000u) + acc[ai][bj][m][e >> 1][(2 * e + 1) & 3]; }
; #pragma unroll
;                     for (int e = 0; e < 8; ++e) s += v[e] * v[e];
;                     u32x4 w; w.x = cvt_pk_bf16(v[0], v[1]); w.y = cvt_pk_bf16(v[2], v[3]); w.z = cvt_pk_bf16(v[4], v[5]); w.w = cvt_pk_bf16(v[6], v[7]);
;                     *(u32x4*)(rp + bj * HALF) = w; }
;                 s = sum_x32(sum_x16(s)); asm volatile("" : "+v"(s));
;                 if (fq == 0) atomicAdd(ss + row, s); }
;     }
.LBB0_540:
	v_lshl_add_u32 v156, s61, 8, v170
	v_ashrrev_i32_e32 v157, 31, v156
	v_lshl_or_b32 v154, s60, 8, v172
	v_lshlrev_b64 v[176:177], 12, v[156:157]
	v_ashrrev_i32_e32 v155, 31, v154
	v_lshl_add_u64 v[176:177], s[16:17], 0, v[176:177]
	v_lshl_add_u64 v[180:181], v[154:155], 1, v[176:177]
	global_load_dwordx4 v[176:179], v[180:181], off
	global_load_dwordx4 v[186:189], v[180:181], off offset:256
	s_waitcnt vmcnt(1)
	v_lshlrev_b32_e32 v182, 16, v176
	v_and_b32_e32 v176, 0xffff0000, v176
	v_lshlrev_b32_e32 v183, 16, v177
	v_and_b32_e32 v177, 0xffff0000, v177
	v_lshlrev_b32_e32 v184, 16, v178
	v_and_b32_e32 v178, 0xffff0000, v178
	v_lshlrev_b32_e32 v185, 16, v179
	v_and_b32_e32 v179, 0xffff0000, v179
	v_add_f32_e32 v182, v126, v182
	v_add_f32_e32 v176, v127, v176
	v_add_f32_e32 v183, v128, v183
	v_add_f32_e32 v177, v129, v177
	v_add_f32_e32 v184, v122, v184
	v_add_f32_e32 v178, v123, v178
	v_add_f32_e32 v185, v124, v185
	v_add_f32_e32 v179, v125, v179
	v_cvt_pk_bf16_f32 v122, v182, v176
	v_cvt_pk_bf16_f32 v123, v183, v177
	v_cvt_pk_bf16_f32 v124, v184, v178
	v_cvt_pk_bf16_f32 v125, v185, v179
	s_nop 0
	v_mul_f32_e32 v176, v176, v176
	v_fmac_f32_e32 v176, v182, v182
	v_fmac_f32_e32 v176, v183, v183
	v_fmac_f32_e32 v176, v177, v177
	v_fmac_f32_e32 v176, v184, v184
	v_fmac_f32_e32 v176, v178, v178
	global_store_dwordx4 v[180:181], v[122:125], off
	v_fmac_f32_e32 v176, v185, v185
	v_fmac_f32_e32 v176, v179, v179
	s_waitcnt vmcnt(1)
	v_mov_b32_e32 v126, v186
	v_mov_b32_e32 v127, v187
	v_mov_b32_e32 v128, v188
	v_mov_b32_e32 v129, v189
	v_lshlrev_b32_e32 v122, 16, v126
	v_and_b32_e32 v123, 0xffff0000, v126
	v_add_f32_e32 v118, v118, v122
	v_lshlrev_b32_e32 v124, 16, v127
	v_add_f32_e32 v119, v119, v123
	v_fmac_f32_e32 v176, v118, v118
	v_and_b32_e32 v125, 0xffff0000, v127
	v_add_f32_e32 v120, v120, v124
	v_fmac_f32_e32 v176, v119, v119
	v_lshlrev_b32_e32 v126, 16, v128
	v_add_f32_e32 v121, v121, v125
	v_fmac_f32_e32 v176, v120, v120
	v_and_b32_e32 v127, 0xffff0000, v128
	v_add_f32_e32 v122, v114, v126
	v_fmac_f32_e32 v176, v121, v121
	v_lshlrev_b32_e32 v128, 16, v129
	v_add_f32_e32 v123, v115, v127
	v_fmac_f32_e32 v176, v122, v122
	v_and_b32_e32 v129, 0xffff0000, v129
	v_add_f32_e32 v124, v116, v128
	v_fmac_f32_e32 v176, v123, v123
	v_add_f32_e32 v125, v117, v129
	v_fmac_f32_e32 v176, v124, v124
	v_cvt_pk_bf16_f32 v114, v118, v119
	v_fmac_f32_e32 v176, v125, v125
	v_cvt_pk_bf16_f32 v115, v120, v121
	v_cvt_pk_bf16_f32 v116, v122, v123
	v_cvt_pk_bf16_f32 v117, v124, v125
	global_store_dwordx4 v[180:181], v[114:117], off offset:256
	s_nop 1
	v_mov_b32_e32 v114, v176
	s_nop 1
	v_permlane16_swap_b32_e32 v176, v114
	v_add_f32_e32 v114, v176, v114
	v_mov_b32_e32 v115, v114
	s_nop 1
	v_permlane32_swap_b32_e32 v114, v115
	v_add_f32_e32 v114, v114, v115
	v_mov_b32_e32 v200, v114
	v_lshl_add_u64 v[208:209], v[156:157], 2, s[22:23]
	v_or_b32_e32 v114, 16, v156
	v_ashrrev_i32_e32 v115, 31, v114
	v_lshlrev_b64 v[116:117], 12, v[114:115]
	v_lshl_add_u64 v[116:117], s[16:17], 0, v[116:117]
	v_lshl_add_u64 v[120:121], v[154:155], 1, v[116:117]
	global_load_dwordx4 v[116:119], v[120:121], off
	global_load_dwordx4 v[186:189], v[120:121], off offset:256
	s_waitcnt vmcnt(1)
	v_lshlrev_b32_e32 v122, 16, v116
	v_and_b32_e32 v116, 0xffff0000, v116
	v_lshlrev_b32_e32 v123, 16, v117
	v_and_b32_e32 v117, 0xffff0000, v117
	v_lshlrev_b32_e32 v124, 16, v118
	v_and_b32_e32 v118, 0xffff0000, v118
	v_lshlrev_b32_e32 v125, 16, v119
	v_and_b32_e32 v119, 0xffff0000, v119
	v_add_f32_e32 v122, v110, v122
	v_add_f32_e32 v116, v111, v116
	v_add_f32_e32 v123, v112, v123
	v_add_f32_e32 v117, v113, v117
	v_add_f32_e32 v124, v106, v124
	v_add_f32_e32 v118, v107, v118
	v_add_f32_e32 v125, v108, v125
	v_add_f32_e32 v119, v109, v119
	v_cvt_pk_bf16_f32 v106, v122, v116
	v_cvt_pk_bf16_f32 v107, v123, v117
	v_cvt_pk_bf16_f32 v108, v124, v118
	v_cvt_pk_bf16_f32 v109, v125, v119
	s_nop 0
	v_mul_f32_e32 v116, v116, v116
	v_fmac_f32_e32 v116, v122, v122
	v_fmac_f32_e32 v116, v123, v123
	v_fmac_f32_e32 v116, v117, v117
	v_fmac_f32_e32 v116, v124, v124
	v_fmac_f32_e32 v116, v118, v118
	global_store_dwordx4 v[120:121], v[106:109], off
	v_fmac_f32_e32 v116, v125, v125
	v_fmac_f32_e32 v116, v119, v119
	s_waitcnt vmcnt(1)
	v_mov_b32_e32 v110, v186
	v_mov_b32_e32 v111, v187
	v_mov_b32_e32 v112, v188
	v_mov_b32_e32 v113, v189
	v_lshlrev_b32_e32 v106, 16, v110
	v_and_b32_e32 v107, 0xffff0000, v110
	v_add_f32_e32 v102, v102, v106
	v_lshlrev_b32_e32 v108, 16, v111
	v_add_f32_e32 v103, v103, v107
	v_fmac_f32_e32 v116, v102, v102
	v_and_b32_e32 v109, 0xffff0000, v111
	v_add_f32_e32 v104, v104, v108
	v_fmac_f32_e32 v116, v103, v103
	v_lshlrev_b32_e32 v110, 16, v112
	v_add_f32_e32 v105, v105, v109
	v_fmac_f32_e32 v116, v104, v104
	v_and_b32_e32 v111, 0xffff0000, v112
	v_add_f32_e32 v106, v98, v110
	v_fmac_f32_e32 v116, v105, v105
	v_lshlrev_b32_e32 v112, 16, v113
	v_add_f32_e32 v107, v99, v111
	v_fmac_f32_e32 v116, v106, v106
	v_and_b32_e32 v113, 0xffff0000, v113
	v_add_f32_e32 v108, v100, v112
	v_fmac_f32_e32 v116, v107, v107
	v_add_f32_e32 v109, v101, v113
	v_fmac_f32_e32 v116, v108, v108
	v_cvt_pk_bf16_f32 v98, v102, v103
	v_fmac_f32_e32 v116, v109, v109
	v_cvt_pk_bf16_f32 v99, v104, v105
	v_cvt_pk_bf16_f32 v100, v106, v107
	v_cvt_pk_bf16_f32 v101, v108, v109
	global_store_dwordx4 v[120:121], v[98:101], off offset:256
	s_nop 1
	v_mov_b32_e32 v98, v116
	s_nop 1
	v_permlane16_swap_b32_e32 v116, v98
	v_add_f32_e32 v98, v116, v98
	v_mov_b32_e32 v99, v98
	s_nop 1
	v_permlane32_swap_b32_e32 v98, v99
	v_add_f32_e32 v98, v98, v99
	v_mov_b32_e32 v201, v98
	v_or_b32_e32 v98, 32, v156
	v_ashrrev_i32_e32 v99, 31, v98
	v_lshlrev_b64 v[100:101], 12, v[98:99]
	v_lshl_add_u64 v[100:101], s[16:17], 0, v[100:101]
	v_lshl_add_u64 v[104:105], v[154:155], 1, v[100:101]
	global_load_dwordx4 v[100:103], v[104:105], off
	global_load_dwordx4 v[186:189], v[104:105], off offset:256
	s_waitcnt vmcnt(1)
; __device__ __forceinline__ unsigned cvt_pk_bf16(float lo, float hi) { unsigned r; asm volatile("v_cvt_pk_bf16_f32 %0, %1, %2" : "=v"(r) : "v"(lo), "v"(hi)); return r; }
;     __device__ __forceinline__ void operator()(const f32x4 (&acc)[2][2][4][2], const Unit& u, int wr, int wc, int fr, int fq) const {
;     ...
;             for (int m = 0; m < 4; ++m) { const int row = row0 + ai * HALF + m * 16; bf16_t* rp = xb + (size_t)row * 2048 + col0; float s = 0.f;
; #pragma unroll
;                 for (int bj = 0; bj < 2; ++bj) { const u32x4 x = *(const u32x4*)(rp + bj * HALF); float v[8];
; #pragma unroll
;                     for (int e = 0; e < 4; ++e) { v[2 * e] = __builtin_bit_cast(float, x[e] << 16) + acc[ai][bj][m][e >> 1][(2 * e) & 3]; v[2 * e + 1] = __builtin_bit_cast(float, x[e] & 0xffff0000u) + acc[ai][bj][m][e >> 1][(2 * e + 1) & 3]; }
; #pragma unroll
;                     for (int e = 0; e < 8; ++e) s += v[e] * v[e];
;                     u32x4 w; w.x = cvt_pk_bf16(v[0], v[1]); w.y = cvt_pk_bf16(v[2], v[3]); w.z = cvt_pk_bf16(v[4], v[5]); w.w = cvt_pk_bf16(v[6], v[7]);
;                     *(u32x4*)(rp + bj * HALF) = w; }
;                 s = sum_x32(sum_x16(s)); asm volatile("" : "+v"(s));
;                 if (fq == 0) atomicAdd(ss + row, s); }
	v_lshlrev_b32_e32 v106, 16, v100
	v_and_b32_e32 v100, 0xffff0000, v100
	v_lshlrev_b32_e32 v107, 16, v101
	v_and_b32_e32 v101, 0xffff0000, v101
	v_lshlrev_b32_e32 v108, 16, v102
	v_and_b32_e32 v102, 0xffff0000, v102
	v_lshlrev_b32_e32 v109, 16, v103
	v_and_b32_e32 v103, 0xffff0000, v103
	v_add_f32_e32 v106, v94, v106
	v_add_f32_e32 v100, v95, v100
	v_add_f32_e32 v107, v96, v107
	v_add_f32_e32 v101, v97, v101
	v_add_f32_e32 v108, v90, v108
	v_add_f32_e32 v102, v91, v102
	v_add_f32_e32 v109, v92, v109
	v_add_f32_e32 v103, v93, v103
	v_cvt_pk_bf16_f32 v90, v106, v100
	v_cvt_pk_bf16_f32 v91, v107, v101
	v_cvt_pk_bf16_f32 v92, v108, v102
	v_cvt_pk_bf16_f32 v93, v109, v103
	s_nop 0
	v_mul_f32_e32 v100, v100, v100
	v_fmac_f32_e32 v100, v106, v106
	v_fmac_f32_e32 v100, v107, v107
	v_fmac_f32_e32 v100, v101, v101
	v_fmac_f32_e32 v100, v108, v108
	v_fmac_f32_e32 v100, v102, v102
	global_store_dwordx4 v[104:105], v[90:93], off
	v_fmac_f32_e32 v100, v109, v109
	v_fmac_f32_e32 v100, v103, v103
	s_waitcnt vmcnt(1)
	v_mov_b32_e32 v94, v186
	v_mov_b32_e32 v95, v187
	v_mov_b32_e32 v96, v188
	v_mov_b32_e32 v97, v189
	v_lshlrev_b32_e32 v90, 16, v94
	v_and_b32_e32 v91, 0xffff0000, v94
	v_add_f32_e32 v86, v86, v90
	v_lshlrev_b32_e32 v92, 16, v95
	v_add_f32_e32 v87, v87, v91
	v_fmac_f32_e32 v100, v86, v86
	v_and_b32_e32 v93, 0xffff0000, v95
	v_add_f32_e32 v88, v88, v92
	v_fmac_f32_e32 v100, v87, v87
	v_lshlrev_b32_e32 v94, 16, v96
	v_add_f32_e32 v89, v89, v93
	v_fmac_f32_e32 v100, v88, v88
	v_and_b32_e32 v95, 0xffff0000, v96
	v_add_f32_e32 v90, v82, v94
	v_fmac_f32_e32 v100, v89, v89
	v_lshlrev_b32_e32 v96, 16, v97
	v_add_f32_e32 v91, v83, v95
	v_fmac_f32_e32 v100, v90, v90
	v_and_b32_e32 v97, 0xffff0000, v97
	v_add_f32_e32 v92, v84, v96
	v_fmac_f32_e32 v100, v91, v91
	v_add_f32_e32 v93, v85, v97
	v_fmac_f32_e32 v100, v92, v92
	v_cvt_pk_bf16_f32 v82, v86, v87
	v_fmac_f32_e32 v100, v93, v93
	v_cvt_pk_bf16_f32 v83, v88, v89
	v_cvt_pk_bf16_f32 v84, v90, v91
	v_cvt_pk_bf16_f32 v85, v92, v93
	global_store_dwordx4 v[104:105], v[82:85], off offset:256
	s_nop 1
	v_mov_b32_e32 v82, v100
	s_nop 1
	v_permlane16_swap_b32_e32 v100, v82
	v_add_f32_e32 v82, v100, v82
	v_mov_b32_e32 v83, v82
	s_nop 1
	v_permlane32_swap_b32_e32 v82, v83
	v_add_f32_e32 v82, v82, v83
	v_mov_b32_e32 v202, v82
	v_or_b32_e32 v82, 48, v156
	v_ashrrev_i32_e32 v83, 31, v82
	v_lshlrev_b64 v[84:85], 12, v[82:83]
	v_lshl_add_u64 v[84:85], s[16:17], 0, v[84:85]
	v_lshl_add_u64 v[88:89], v[154:155], 1, v[84:85]
	global_load_dwordx4 v[84:87], v[88:89], off
	global_load_dwordx4 v[186:189], v[88:89], off offset:256
	s_waitcnt vmcnt(1)
	v_lshlrev_b32_e32 v90, 16, v84
	v_and_b32_e32 v84, 0xffff0000, v84
	v_lshlrev_b32_e32 v91, 16, v85
	v_and_b32_e32 v85, 0xffff0000, v85
	v_lshlrev_b32_e32 v92, 16, v86
	v_and_b32_e32 v86, 0xffff0000, v86
	v_lshlrev_b32_e32 v93, 16, v87
	v_and_b32_e32 v87, 0xffff0000, v87
	v_add_f32_e32 v90, v78, v90
	v_add_f32_e32 v84, v79, v84
	v_add_f32_e32 v91, v80, v91
	v_add_f32_e32 v85, v81, v85
	v_add_f32_e32 v92, v74, v92
	v_add_f32_e32 v86, v75, v86
	v_add_f32_e32 v93, v76, v93
	v_add_f32_e32 v87, v77, v87
	v_cvt_pk_bf16_f32 v74, v90, v84
	v_cvt_pk_bf16_f32 v75, v91, v85
	v_cvt_pk_bf16_f32 v76, v92, v86
	v_cvt_pk_bf16_f32 v77, v93, v87
	s_nop 0
	v_mul_f32_e32 v84, v84, v84
	v_fmac_f32_e32 v84, v90, v90
	v_fmac_f32_e32 v84, v91, v91
	v_fmac_f32_e32 v84, v85, v85
	v_fmac_f32_e32 v84, v92, v92
	v_fmac_f32_e32 v84, v86, v86
	global_store_dwordx4 v[88:89], v[74:77], off
	v_fmac_f32_e32 v84, v93, v93
	v_fmac_f32_e32 v84, v87, v87
	s_waitcnt vmcnt(1)
	v_mov_b32_e32 v78, v186
	v_mov_b32_e32 v79, v187
	v_mov_b32_e32 v80, v188
	v_mov_b32_e32 v81, v189
	v_lshlrev_b32_e32 v74, 16, v78
	v_and_b32_e32 v75, 0xffff0000, v78
	v_add_f32_e32 v70, v70, v74
	v_lshlrev_b32_e32 v76, 16, v79
	v_add_f32_e32 v71, v71, v75
	v_fmac_f32_e32 v84, v70, v70
	v_and_b32_e32 v77, 0xffff0000, v79
	v_add_f32_e32 v72, v72, v76
	v_fmac_f32_e32 v84, v71, v71
	v_lshlrev_b32_e32 v78, 16, v80
	v_add_f32_e32 v73, v73, v77
	v_fmac_f32_e32 v84, v72, v72
	v_and_b32_e32 v79, 0xffff0000, v80
	v_add_f32_e32 v74, v66, v78
	v_fmac_f32_e32 v84, v73, v73
	v_lshlrev_b32_e32 v80, 16, v81
	v_add_f32_e32 v75, v67, v79
	v_fmac_f32_e32 v84, v74, v74
	v_and_b32_e32 v81, 0xffff0000, v81
	v_add_f32_e32 v76, v68, v80
	v_fmac_f32_e32 v84, v75, v75
	v_add_f32_e32 v77, v69, v81
	v_fmac_f32_e32 v84, v76, v76
	v_cvt_pk_bf16_f32 v66, v70, v71
	v_fmac_f32_e32 v84, v77, v77
	v_cvt_pk_bf16_f32 v67, v72, v73
	v_cvt_pk_bf16_f32 v68, v74, v75
	v_cvt_pk_bf16_f32 v69, v76, v77
	global_store_dwordx4 v[88:89], v[66:69], off offset:256
	s_nop 1
	v_mov_b32_e32 v66, v84
	s_nop 1
	v_permlane16_swap_b32_e32 v84, v66
	v_add_f32_e32 v66, v84, v66
	v_mov_b32_e32 v67, v66
	s_nop 1
	v_permlane32_swap_b32_e32 v66, v67
	v_add_f32_e32 v66, v66, v67
	v_mov_b32_e32 v203, v66
	v_add_u32_e32 v66, 0x80, v156
	v_ashrrev_i32_e32 v67, 31, v66
	v_lshlrev_b64 v[68:69], 12, v[66:67]
	v_lshl_add_u64 v[68:69], s[16:17], 0, v[68:69]
	v_lshl_add_u64 v[72:73], v[154:155], 1, v[68:69]
	global_load_dwordx4 v[68:71], v[72:73], off
	global_load_dwordx4 v[186:189], v[72:73], off offset:256
	s_waitcnt vmcnt(1)
	v_lshlrev_b32_e32 v74, 16, v68
	v_and_b32_e32 v68, 0xffff0000, v68
	v_lshlrev_b32_e32 v75, 16, v69
	v_and_b32_e32 v69, 0xffff0000, v69
	v_lshlrev_b32_e32 v76, 16, v70
	v_and_b32_e32 v70, 0xffff0000, v70
	v_lshlrev_b32_e32 v77, 16, v71
	v_and_b32_e32 v71, 0xffff0000, v71
	v_add_f32_e32 v74, v62, v74
	v_add_f32_e32 v68, v63, v68
	v_add_f32_e32 v75, v64, v75
	v_add_f32_e32 v69, v65, v69
	v_add_f32_e32 v76, v58, v76
	v_add_f32_e32 v70, v59, v70
	v_add_f32_e32 v77, v60, v77
	v_add_f32_e32 v71, v61, v71
	v_cvt_pk_bf16_f32 v58, v74, v68
	v_cvt_pk_bf16_f32 v59, v75, v69
	v_cvt_pk_bf16_f32 v60, v76, v70
	v_cvt_pk_bf16_f32 v61, v77, v71
	s_nop 0
	v_mul_f32_e32 v68, v68, v68
	v_fmac_f32_e32 v68, v74, v74
	v_fmac_f32_e32 v68, v75, v75
	v_fmac_f32_e32 v68, v69, v69
	v_fmac_f32_e32 v68, v76, v76
	v_fmac_f32_e32 v68, v70, v70
	global_store_dwordx4 v[72:73], v[58:61], off
	v_fmac_f32_e32 v68, v77, v77
	v_fmac_f32_e32 v68, v71, v71
	s_waitcnt vmcnt(1)
; __device__ __forceinline__ unsigned cvt_pk_bf16(float lo, float hi) { unsigned r; asm volatile("v_cvt_pk_bf16_f32 %0, %1, %2" : "=v"(r) : "v"(lo), "v"(hi)); return r; }
;     __device__ __forceinline__ void operator()(const f32x4 (&acc)[2][2][4][2], const Unit& u, int wr, int wc, int fr, int fq) const {
;     ...
;             for (int m = 0; m < 4; ++m) { const int row = row0 + ai * HALF + m * 16; bf16_t* rp = xb + (size_t)row * 2048 + col0; float s = 0.f;
; #pragma unroll
;                 for (int bj = 0; bj < 2; ++bj) { const u32x4 x = *(const u32x4*)(rp + bj * HALF); float v[8];
; #pragma unroll
;                     for (int e = 0; e < 4; ++e) { v[2 * e] = __builtin_bit_cast(float, x[e] << 16) + acc[ai][bj][m][e >> 1][(2 * e) & 3]; v[2 * e + 1] = __builtin_bit_cast(float, x[e] & 0xffff0000u) + acc[ai][bj][m][e >> 1][(2 * e + 1) & 3]; }
; #pragma unroll
;                     for (int e = 0; e < 8; ++e) s += v[e] * v[e];
;                     u32x4 w; w.x = cvt_pk_bf16(v[0], v[1]); w.y = cvt_pk_bf16(v[2], v[3]); w.z = cvt_pk_bf16(v[4], v[5]); w.w = cvt_pk_bf16(v[6], v[7]);
;                     *(u32x4*)(rp + bj * HALF) = w; }
;                 s = sum_x32(sum_x16(s)); asm volatile("" : "+v"(s));
;                 if (fq == 0) atomicAdd(ss + row, s); }
	v_mov_b32_e32 v62, v186
	v_mov_b32_e32 v63, v187
	v_mov_b32_e32 v64, v188
	v_mov_b32_e32 v65, v189
	v_lshlrev_b32_e32 v58, 16, v62
	v_and_b32_e32 v59, 0xffff0000, v62
	v_add_f32_e32 v54, v54, v58
	v_lshlrev_b32_e32 v60, 16, v63
	v_add_f32_e32 v55, v55, v59
	v_fmac_f32_e32 v68, v54, v54
	v_and_b32_e32 v61, 0xffff0000, v63
	v_add_f32_e32 v56, v56, v60
	v_fmac_f32_e32 v68, v55, v55
	v_lshlrev_b32_e32 v62, 16, v64
	v_add_f32_e32 v57, v57, v61
	v_fmac_f32_e32 v68, v56, v56
	v_and_b32_e32 v63, 0xffff0000, v64
	v_add_f32_e32 v58, v50, v62
	v_fmac_f32_e32 v68, v57, v57
	v_lshlrev_b32_e32 v64, 16, v65
	v_add_f32_e32 v59, v51, v63
	v_fmac_f32_e32 v68, v58, v58
	v_and_b32_e32 v65, 0xffff0000, v65
	v_add_f32_e32 v60, v52, v64
	v_fmac_f32_e32 v68, v59, v59
	v_add_f32_e32 v61, v53, v65
	v_fmac_f32_e32 v68, v60, v60
	v_cvt_pk_bf16_f32 v50, v54, v55
	v_fmac_f32_e32 v68, v61, v61
	v_cvt_pk_bf16_f32 v51, v56, v57
	v_cvt_pk_bf16_f32 v52, v58, v59
	v_cvt_pk_bf16_f32 v53, v60, v61
	global_store_dwordx4 v[72:73], v[50:53], off offset:256
	s_nop 1
	v_mov_b32_e32 v50, v68
	s_nop 1
	v_permlane16_swap_b32_e32 v68, v50
	v_add_f32_e32 v50, v68, v50
	v_mov_b32_e32 v51, v50
	s_nop 1
	v_permlane32_swap_b32_e32 v50, v51
	v_add_f32_e32 v50, v50, v51
	v_mov_b32_e32 v204, v50
	v_add_u32_e32 v50, 0x90, v156
	v_ashrrev_i32_e32 v51, 31, v50
	v_lshlrev_b64 v[52:53], 12, v[50:51]
	v_lshl_add_u64 v[52:53], s[16:17], 0, v[52:53]
	v_lshl_add_u64 v[56:57], v[154:155], 1, v[52:53]
	global_load_dwordx4 v[52:55], v[56:57], off
	global_load_dwordx4 v[186:189], v[56:57], off offset:256
	s_waitcnt vmcnt(1)
	v_lshlrev_b32_e32 v58, 16, v52
	v_and_b32_e32 v52, 0xffff0000, v52
	v_lshlrev_b32_e32 v59, 16, v53
	v_and_b32_e32 v53, 0xffff0000, v53
	v_lshlrev_b32_e32 v60, 16, v54
	v_and_b32_e32 v54, 0xffff0000, v54
	v_lshlrev_b32_e32 v61, 16, v55
	v_and_b32_e32 v55, 0xffff0000, v55
	v_add_f32_e32 v58, v46, v58
	v_add_f32_e32 v52, v47, v52
	v_add_f32_e32 v59, v48, v59
	v_add_f32_e32 v53, v49, v53
	v_add_f32_e32 v60, v42, v60
	v_add_f32_e32 v54, v43, v54
	v_add_f32_e32 v61, v44, v61
	v_add_f32_e32 v55, v45, v55
	v_cvt_pk_bf16_f32 v42, v58, v52
	v_cvt_pk_bf16_f32 v43, v59, v53
	v_cvt_pk_bf16_f32 v44, v60, v54
	v_cvt_pk_bf16_f32 v45, v61, v55
	s_nop 0
	v_mul_f32_e32 v52, v52, v52
	v_fmac_f32_e32 v52, v58, v58
	v_fmac_f32_e32 v52, v59, v59
	v_fmac_f32_e32 v52, v53, v53
	v_fmac_f32_e32 v52, v60, v60
	v_fmac_f32_e32 v52, v54, v54
	global_store_dwordx4 v[56:57], v[42:45], off
	v_fmac_f32_e32 v52, v61, v61
	v_fmac_f32_e32 v52, v55, v55
	s_waitcnt vmcnt(1)
	v_mov_b32_e32 v46, v186
	v_mov_b32_e32 v47, v187
	v_mov_b32_e32 v48, v188
	v_mov_b32_e32 v49, v189
	v_lshlrev_b32_e32 v42, 16, v46
	v_and_b32_e32 v43, 0xffff0000, v46
	v_add_f32_e32 v38, v38, v42
	v_lshlrev_b32_e32 v44, 16, v47
	v_add_f32_e32 v39, v39, v43
	v_fmac_f32_e32 v52, v38, v38
	v_and_b32_e32 v45, 0xffff0000, v47
	v_add_f32_e32 v40, v40, v44
	v_fmac_f32_e32 v52, v39, v39
	v_lshlrev_b32_e32 v46, 16, v48
	v_add_f32_e32 v41, v41, v45
	v_fmac_f32_e32 v52, v40, v40
	v_and_b32_e32 v47, 0xffff0000, v48
	v_add_f32_e32 v42, v34, v46
	v_fmac_f32_e32 v52, v41, v41
	v_lshlrev_b32_e32 v48, 16, v49
	v_add_f32_e32 v43, v35, v47
	v_fmac_f32_e32 v52, v42, v42
	v_and_b32_e32 v49, 0xffff0000, v49
	v_add_f32_e32 v44, v36, v48
	v_fmac_f32_e32 v52, v43, v43
	v_add_f32_e32 v45, v37, v49
	v_fmac_f32_e32 v52, v44, v44
	v_cvt_pk_bf16_f32 v34, v38, v39
	v_fmac_f32_e32 v52, v45, v45
	v_cvt_pk_bf16_f32 v35, v40, v41
	v_cvt_pk_bf16_f32 v36, v42, v43
	v_cvt_pk_bf16_f32 v37, v44, v45
	global_store_dwordx4 v[56:57], v[34:37], off offset:256
	s_nop 1
	v_mov_b32_e32 v34, v52
	s_nop 1
	v_permlane16_swap_b32_e32 v52, v34
	v_add_f32_e32 v34, v52, v34
	v_mov_b32_e32 v35, v34
	s_nop 1
	v_permlane32_swap_b32_e32 v34, v35
	v_add_f32_e32 v34, v34, v35
	v_mov_b32_e32 v205, v34
	v_add_u32_e32 v34, 0xa0, v156
	v_ashrrev_i32_e32 v35, 31, v34
	v_lshlrev_b64 v[36:37], 12, v[34:35]
	v_lshl_add_u64 v[36:37], s[16:17], 0, v[36:37]
	v_lshl_add_u64 v[40:41], v[154:155], 1, v[36:37]
	global_load_dwordx4 v[36:39], v[40:41], off
	global_load_dwordx4 v[186:189], v[40:41], off offset:256
	s_waitcnt vmcnt(1)
	v_lshlrev_b32_e32 v42, 16, v36
	v_and_b32_e32 v36, 0xffff0000, v36
	v_lshlrev_b32_e32 v43, 16, v37
	v_and_b32_e32 v37, 0xffff0000, v37
	v_lshlrev_b32_e32 v44, 16, v38
	v_and_b32_e32 v38, 0xffff0000, v38
	v_lshlrev_b32_e32 v45, 16, v39
	v_and_b32_e32 v39, 0xffff0000, v39
	v_add_f32_e32 v42, v30, v42
	v_add_f32_e32 v36, v31, v36
	v_add_f32_e32 v43, v32, v43
	v_add_f32_e32 v37, v33, v37
	v_add_f32_e32 v44, v26, v44
	v_add_f32_e32 v38, v27, v38
	v_add_f32_e32 v45, v28, v45
	v_add_f32_e32 v39, v29, v39
	v_cvt_pk_bf16_f32 v26, v42, v36
	v_cvt_pk_bf16_f32 v27, v43, v37
	v_cvt_pk_bf16_f32 v28, v44, v38
	v_cvt_pk_bf16_f32 v29, v45, v39
	s_nop 0
	v_mul_f32_e32 v36, v36, v36
	v_fmac_f32_e32 v36, v42, v42
	v_fmac_f32_e32 v36, v43, v43
	v_fmac_f32_e32 v36, v37, v37
	v_fmac_f32_e32 v36, v44, v44
	v_fmac_f32_e32 v36, v38, v38
	global_store_dwordx4 v[40:41], v[26:29], off
	v_fmac_f32_e32 v36, v45, v45
	v_fmac_f32_e32 v36, v39, v39
	s_waitcnt vmcnt(1)
; __device__ __forceinline__ unsigned cvt_pk_bf16(float lo, float hi) { unsigned r; asm volatile("v_cvt_pk_bf16_f32 %0, %1, %2" : "=v"(r) : "v"(lo), "v"(hi)); return r; }
;     __device__ __forceinline__ void operator()(const f32x4 (&acc)[2][2][4][2], const Unit& u, int wr, int wc, int fr, int fq) const {
;     ...
;             for (int m = 0; m < 4; ++m) { const int row = row0 + ai * HALF + m * 16; bf16_t* rp = xb + (size_t)row * 2048 + col0; float s = 0.f;
; #pragma unroll
;                 for (int bj = 0; bj < 2; ++bj) { const u32x4 x = *(const u32x4*)(rp + bj * HALF); float v[8];
; #pragma unroll
;                     for (int e = 0; e < 4; ++e) { v[2 * e] = __builtin_bit_cast(float, x[e] << 16) + acc[ai][bj][m][e >> 1][(2 * e) & 3]; v[2 * e + 1] = __builtin_bit_cast(float, x[e] & 0xffff0000u) + acc[ai][bj][m][e >> 1][(2 * e + 1) & 3]; }
; #pragma unroll
;                     for (int e = 0; e < 8; ++e) s += v[e] * v[e];
;                     u32x4 w; w.x = cvt_pk_bf16(v[0], v[1]); w.y = cvt_pk_bf16(v[2], v[3]); w.z = cvt_pk_bf16(v[4], v[5]); w.w = cvt_pk_bf16(v[6], v[7]);
;                     *(u32x4*)(rp + bj * HALF) = w; }
;                 s = sum_x32(sum_x16(s)); asm volatile("" : "+v"(s));
;                 if (fq == 0) atomicAdd(ss + row, s); }
	v_mov_b32_e32 v30, v186
	v_mov_b32_e32 v31, v187
	v_mov_b32_e32 v32, v188
	v_mov_b32_e32 v33, v189
	v_lshlrev_b32_e32 v26, 16, v30
	v_and_b32_e32 v27, 0xffff0000, v30
	v_add_f32_e32 v22, v22, v26
	v_lshlrev_b32_e32 v28, 16, v31
	v_add_f32_e32 v23, v23, v27
	v_fmac_f32_e32 v36, v22, v22
	v_and_b32_e32 v29, 0xffff0000, v31
	v_add_f32_e32 v24, v24, v28
	v_fmac_f32_e32 v36, v23, v23
	v_lshlrev_b32_e32 v30, 16, v32
	v_add_f32_e32 v25, v25, v29
	v_fmac_f32_e32 v36, v24, v24
	v_and_b32_e32 v31, 0xffff0000, v32
	v_add_f32_e32 v26, v18, v30
	v_fmac_f32_e32 v36, v25, v25
	v_lshlrev_b32_e32 v32, 16, v33
	v_add_f32_e32 v27, v19, v31
	v_fmac_f32_e32 v36, v26, v26
	v_and_b32_e32 v33, 0xffff0000, v33
	v_add_f32_e32 v28, v20, v32
	v_fmac_f32_e32 v36, v27, v27
	v_add_f32_e32 v29, v21, v33
	v_fmac_f32_e32 v36, v28, v28
	v_cvt_pk_bf16_f32 v18, v22, v23
	v_fmac_f32_e32 v36, v29, v29
	v_cvt_pk_bf16_f32 v19, v24, v25
	v_cvt_pk_bf16_f32 v20, v26, v27
	v_cvt_pk_bf16_f32 v21, v28, v29
	global_store_dwordx4 v[40:41], v[18:21], off offset:256
	s_nop 1
	v_mov_b32_e32 v18, v36
	s_nop 1
	v_permlane16_swap_b32_e32 v36, v18
	v_add_f32_e32 v18, v36, v18
	v_mov_b32_e32 v19, v18
	s_nop 1
	v_permlane32_swap_b32_e32 v18, v19
	v_add_f32_e32 v18, v18, v19
	v_mov_b32_e32 v206, v18
	v_add_u32_e32 v18, 0xb0, v156
	v_ashrrev_i32_e32 v19, 31, v18
	v_lshlrev_b64 v[20:21], 12, v[18:19]
	v_lshl_add_u64 v[20:21], s[16:17], 0, v[20:21]
	v_lshl_add_u64 v[24:25], v[154:155], 1, v[20:21]
	global_load_dwordx4 v[20:23], v[24:25], off
	global_load_dwordx4 v[186:189], v[24:25], off offset:256
	s_waitcnt vmcnt(1)
	v_lshlrev_b32_e32 v26, 16, v20
	v_and_b32_e32 v20, 0xffff0000, v20
	v_lshlrev_b32_e32 v27, 16, v21
	v_and_b32_e32 v21, 0xffff0000, v21
	v_lshlrev_b32_e32 v28, 16, v22
	v_and_b32_e32 v22, 0xffff0000, v22
	v_lshlrev_b32_e32 v29, 16, v23
	v_and_b32_e32 v23, 0xffff0000, v23
	v_add_f32_e32 v26, v14, v26
	v_add_f32_e32 v20, v15, v20
	v_add_f32_e32 v27, v16, v27
	v_add_f32_e32 v21, v17, v21
	v_add_f32_e32 v28, v10, v28
	v_add_f32_e32 v22, v11, v22
	v_add_f32_e32 v29, v12, v29
	v_add_f32_e32 v23, v13, v23
	v_cvt_pk_bf16_f32 v10, v26, v20
	v_cvt_pk_bf16_f32 v11, v27, v21
	v_cvt_pk_bf16_f32 v12, v28, v22
	v_cvt_pk_bf16_f32 v13, v29, v23
	s_nop 0
	v_mul_f32_e32 v20, v20, v20
	v_fmac_f32_e32 v20, v26, v26
	v_fmac_f32_e32 v20, v27, v27
	v_fmac_f32_e32 v20, v21, v21
	v_fmac_f32_e32 v20, v28, v28
	v_fmac_f32_e32 v20, v22, v22
	global_store_dwordx4 v[24:25], v[10:13], off
	v_fmac_f32_e32 v20, v29, v29
	v_fmac_f32_e32 v20, v23, v23
	s_waitcnt vmcnt(1)
	v_mov_b32_e32 v14, v186
	v_mov_b32_e32 v15, v187
	v_mov_b32_e32 v16, v188
	v_mov_b32_e32 v17, v189
	v_lshlrev_b32_e32 v10, 16, v14
	v_and_b32_e32 v11, 0xffff0000, v14
	v_add_f32_e32 v6, v6, v10
	v_lshlrev_b32_e32 v12, 16, v15
	v_add_f32_e32 v7, v7, v11
	v_fmac_f32_e32 v20, v6, v6
	v_and_b32_e32 v13, 0xffff0000, v15
	v_add_f32_e32 v8, v8, v12
	v_fmac_f32_e32 v20, v7, v7
	v_lshlrev_b32_e32 v14, 16, v16
	v_add_f32_e32 v9, v9, v13
	v_fmac_f32_e32 v20, v8, v8
	v_and_b32_e32 v15, 0xffff0000, v16
	v_add_f32_e32 v10, v2, v14
	v_fmac_f32_e32 v20, v9, v9
	v_lshlrev_b32_e32 v16, 16, v17
	v_add_f32_e32 v11, v3, v15
	v_fmac_f32_e32 v20, v10, v10
	v_and_b32_e32 v17, 0xffff0000, v17
	v_add_f32_e32 v12, v4, v16
	v_fmac_f32_e32 v20, v11, v11
	v_add_f32_e32 v13, v5, v17
	v_fmac_f32_e32 v20, v12, v12
	v_cvt_pk_bf16_f32 v2, v6, v7
	v_fmac_f32_e32 v20, v13, v13
	v_cvt_pk_bf16_f32 v3, v8, v9
	v_cvt_pk_bf16_f32 v4, v10, v11
	v_cvt_pk_bf16_f32 v5, v12, v13
	global_store_dwordx4 v[24:25], v[2:5], off offset:256
	s_nop 1
	v_mov_b32_e32 v2, v20
	s_nop 1
	v_permlane16_swap_b32_e32 v20, v2
	v_add_f32_e32 v2, v20, v2
	v_mov_b32_e32 v3, v2
	s_nop 1
	v_permlane32_swap_b32_e32 v2, v3
	v_add_f32_e32 v2, v2, v3
	v_mov_b32_e32 v207, v2
	s_and_saveexec_b64 s[36:37], s[4:5]
	global_atomic_add_f32 v[208:209], v200, off
	global_atomic_add_f32 v[208:209], v201, off offset:64
	global_atomic_add_f32 v[208:209], v202, off offset:128
	global_atomic_add_f32 v[208:209], v203, off offset:192
	global_atomic_add_f32 v[208:209], v204, off offset:512
	global_atomic_add_f32 v[208:209], v205, off offset:576
	global_atomic_add_f32 v[208:209], v206, off offset:640
	global_atomic_add_f32 v[208:209], v207, off offset:704
	s_or_b64 exec, exec, s[36:37]
	s_and_b64 vcc, exec, s[10:11]
	s_mov_b64 s[10:11], -1
	s_cbranch_vccnz .LBB0_525
	s_andn2_b64 vcc, exec, s[24:25]
	s_cbranch_vccnz .LBB0_524
	s_barrier
	s_branch .LBB0_524

; __device__ __forceinline__ unsigned cvt_pk_bf16(float lo, float hi) { unsigned r; asm volatile("v_cvt_pk_bf16_f32 %0, %1, %2" : "=v"(r) : "v"(lo), "v"(hi)); return r; }
;     __device__ __forceinline__ void operator()(const f32x4 (&acc)[2][2][4][2], const Unit& u, int wr, int wc, int fr, int fq) const {
;     ...
;             for (int m = 0; m < 4; ++m) { const int row = row0 + ai * HALF + m * 16; bf16_t* rp = xb + (size_t)row * 2048 + col0; float s = 0.f;
; #pragma unroll
;                 for (int bj = 0; bj < 2; ++bj) { const u32x4 x = *(const u32x4*)(rp + bj * HALF); float v[8];
; #pragma unroll
;                     for (int e = 0; e < 4; ++e) { v[2 * e] = __builtin_bit_cast(float, x[e] << 16) + acc[ai][bj][m][e >> 1][(2 * e) & 3]; v[2 * e + 1] = __builtin_bit_cast(float, x[e] & 0xffff0000u) + acc[ai][bj][m][e >> 1][(2 * e + 1) & 3]; }
; #pragma unroll
;                     for (int e = 0; e < 8; ++e) s += v[e] * v[e];
;                     u32x4 w; w.x = cvt_pk_bf16(v[0], v[1]); w.y = cvt_pk_bf16(v[2], v[3]); w.z = cvt_pk_bf16(v[4], v[5]); w.w = cvt_pk_bf16(v[6], v[7]);
;                     *(u32x4*)(rp + bj * HALF) = w; }
;                 s = sum_x32(sum_x16(s)); asm volatile("" : "+v"(s));
;                 if (fq == 0) atomicAdd(ss + row, s); }
.LBB0_624:
	v_lshl_add_u32 v148, s52, 8, v151
	v_ashrrev_i32_e32 v149, 31, v148
	v_lshl_or_b32 v146, s51, 8, v152
	v_lshlrev_b64 v[156:157], 12, v[148:149]
	v_ashrrev_i32_e32 v147, 31, v146
	v_lshl_add_u64 v[156:157], s[16:17], 0, v[156:157]
	v_lshl_add_u64 v[160:161], v[146:147], 1, v[156:157]
	global_load_dwordx4 v[156:159], v[160:161], off
	global_load_dwordx4 v[186:189], v[160:161], off offset:256
	s_waitcnt vmcnt(1)
	v_lshlrev_b32_e32 v155, 16, v156
	v_and_b32_e32 v156, 0xffff0000, v156
	v_lshlrev_b32_e32 v162, 16, v157
	v_and_b32_e32 v157, 0xffff0000, v157
	v_lshlrev_b32_e32 v163, 16, v158
	v_and_b32_e32 v158, 0xffff0000, v158
	v_lshlrev_b32_e32 v164, 16, v159
	v_and_b32_e32 v159, 0xffff0000, v159
	v_add_f32_e32 v155, v126, v155
	v_add_f32_e32 v156, v127, v156
	v_add_f32_e32 v162, v128, v162
	v_add_f32_e32 v157, v129, v157
	v_add_f32_e32 v163, v122, v163
	v_add_f32_e32 v158, v123, v158
	v_add_f32_e32 v164, v124, v164
	v_add_f32_e32 v159, v125, v159
	v_cvt_pk_bf16_f32 v122, v155, v156
	v_cvt_pk_bf16_f32 v123, v162, v157
	v_cvt_pk_bf16_f32 v124, v163, v158
	v_cvt_pk_bf16_f32 v125, v164, v159
	s_nop 0
	v_mul_f32_e32 v156, v156, v156
	v_fmac_f32_e32 v156, v155, v155
	v_fmac_f32_e32 v156, v162, v162
	v_fmac_f32_e32 v156, v157, v157
	v_fmac_f32_e32 v156, v163, v163
	v_fmac_f32_e32 v156, v158, v158
	global_store_dwordx4 v[160:161], v[122:125], off
	v_fmac_f32_e32 v156, v164, v164
	v_fmac_f32_e32 v156, v159, v159
	s_waitcnt vmcnt(1)
	v_mov_b32_e32 v126, v186
	v_mov_b32_e32 v127, v187
	v_mov_b32_e32 v128, v188
	v_mov_b32_e32 v129, v189
	v_lshlrev_b32_e32 v122, 16, v126
	v_and_b32_e32 v123, 0xffff0000, v126
	v_add_f32_e32 v118, v118, v122
	v_lshlrev_b32_e32 v124, 16, v127
	v_add_f32_e32 v119, v119, v123
	v_fmac_f32_e32 v156, v118, v118
	v_and_b32_e32 v125, 0xffff0000, v127
	v_add_f32_e32 v120, v120, v124
	v_fmac_f32_e32 v156, v119, v119
	v_lshlrev_b32_e32 v126, 16, v128
	v_add_f32_e32 v121, v121, v125
	v_fmac_f32_e32 v156, v120, v120
	v_and_b32_e32 v127, 0xffff0000, v128
	v_add_f32_e32 v122, v114, v126
	v_fmac_f32_e32 v156, v121, v121
	v_lshlrev_b32_e32 v128, 16, v129
	v_add_f32_e32 v123, v115, v127
	v_fmac_f32_e32 v156, v122, v122
	v_and_b32_e32 v129, 0xffff0000, v129
	v_add_f32_e32 v124, v116, v128
	v_fmac_f32_e32 v156, v123, v123
	v_add_f32_e32 v125, v117, v129
	v_fmac_f32_e32 v156, v124, v124
	v_cvt_pk_bf16_f32 v114, v118, v119
	v_fmac_f32_e32 v156, v125, v125
	v_cvt_pk_bf16_f32 v115, v120, v121
	v_cvt_pk_bf16_f32 v116, v122, v123
	v_cvt_pk_bf16_f32 v117, v124, v125
	global_store_dwordx4 v[160:161], v[114:117], off offset:256
	s_nop 1
	v_mov_b32_e32 v114, v156
	s_nop 1
	v_permlane16_swap_b32_e32 v156, v114
	v_add_f32_e32 v114, v156, v114
	v_mov_b32_e32 v115, v114
	s_nop 1
	v_permlane32_swap_b32_e32 v114, v115
	v_add_f32_e32 v114, v114, v115
	v_mov_b32_e32 v200, v114
	v_lshl_add_u64 v[208:209], v[148:149], 2, s[22:23]
	v_or_b32_e32 v114, 16, v148
	v_ashrrev_i32_e32 v115, 31, v114
	v_lshlrev_b64 v[116:117], 12, v[114:115]
	v_lshl_add_u64 v[116:117], s[16:17], 0, v[116:117]
	v_lshl_add_u64 v[120:121], v[146:147], 1, v[116:117]
	global_load_dwordx4 v[116:119], v[120:121], off
	global_load_dwordx4 v[186:189], v[120:121], off offset:256
	s_waitcnt vmcnt(1)
	v_lshlrev_b32_e32 v122, 16, v116
	v_and_b32_e32 v116, 0xffff0000, v116
	v_lshlrev_b32_e32 v123, 16, v117
	v_and_b32_e32 v117, 0xffff0000, v117
	v_lshlrev_b32_e32 v124, 16, v118
	v_and_b32_e32 v118, 0xffff0000, v118
	v_lshlrev_b32_e32 v125, 16, v119
	v_and_b32_e32 v119, 0xffff0000, v119
	v_add_f32_e32 v122, v110, v122
	v_add_f32_e32 v116, v111, v116
	v_add_f32_e32 v123, v112, v123
	v_add_f32_e32 v117, v113, v117
	v_add_f32_e32 v124, v106, v124
	v_add_f32_e32 v118, v107, v118
	v_add_f32_e32 v125, v108, v125
	v_add_f32_e32 v119, v109, v119
	v_cvt_pk_bf16_f32 v106, v122, v116
	v_cvt_pk_bf16_f32 v107, v123, v117
	v_cvt_pk_bf16_f32 v108, v124, v118
	v_cvt_pk_bf16_f32 v109, v125, v119
	s_nop 0
	v_mul_f32_e32 v116, v116, v116
	v_fmac_f32_e32 v116, v122, v122
	v_fmac_f32_e32 v116, v123, v123
	v_fmac_f32_e32 v116, v117, v117
	v_fmac_f32_e32 v116, v124, v124
	v_fmac_f32_e32 v116, v118, v118
	global_store_dwordx4 v[120:121], v[106:109], off
	v_fmac_f32_e32 v116, v125, v125
	v_fmac_f32_e32 v116, v119, v119
	s_waitcnt vmcnt(1)
	v_mov_b32_e32 v110, v186
	v_mov_b32_e32 v111, v187
	v_mov_b32_e32 v112, v188
	v_mov_b32_e32 v113, v189
	v_lshlrev_b32_e32 v106, 16, v110
	v_and_b32_e32 v107, 0xffff0000, v110
	v_add_f32_e32 v102, v102, v106
	v_lshlrev_b32_e32 v108, 16, v111
	v_add_f32_e32 v103, v103, v107
	v_fmac_f32_e32 v116, v102, v102
	v_and_b32_e32 v109, 0xffff0000, v111
	v_add_f32_e32 v104, v104, v108
	v_fmac_f32_e32 v116, v103, v103
	v_lshlrev_b32_e32 v110, 16, v112
	v_add_f32_e32 v105, v105, v109
	v_fmac_f32_e32 v116, v104, v104
	v_and_b32_e32 v111, 0xffff0000, v112
	v_add_f32_e32 v106, v98, v110
	v_fmac_f32_e32 v116, v105, v105
	v_lshlrev_b32_e32 v112, 16, v113
	v_add_f32_e32 v107, v99, v111
	v_fmac_f32_e32 v116, v106, v106
	v_and_b32_e32 v113, 0xffff0000, v113
	v_add_f32_e32 v108, v100, v112
	v_fmac_f32_e32 v116, v107, v107
	v_add_f32_e32 v109, v101, v113
	v_fmac_f32_e32 v116, v108, v108
	v_cvt_pk_bf16_f32 v98, v102, v103
	v_fmac_f32_e32 v116, v109, v109
	v_cvt_pk_bf16_f32 v99, v104, v105
	v_cvt_pk_bf16_f32 v100, v106, v107
	v_cvt_pk_bf16_f32 v101, v108, v109
	global_store_dwordx4 v[120:121], v[98:101], off offset:256
	s_nop 1
	v_mov_b32_e32 v98, v116
	s_nop 1
	v_permlane16_swap_b32_e32 v116, v98
	v_add_f32_e32 v98, v116, v98
	v_mov_b32_e32 v99, v98
	s_nop 1
	v_permlane32_swap_b32_e32 v98, v99
	v_add_f32_e32 v98, v98, v99
	v_mov_b32_e32 v201, v98
	v_or_b32_e32 v98, 32, v148
	v_ashrrev_i32_e32 v99, 31, v98
	v_lshlrev_b64 v[100:101], 12, v[98:99]
	v_lshl_add_u64 v[100:101], s[16:17], 0, v[100:101]
	v_lshl_add_u64 v[104:105], v[146:147], 1, v[100:101]
	global_load_dwordx4 v[100:103], v[104:105], off
	global_load_dwordx4 v[186:189], v[104:105], off offset:256
	s_waitcnt vmcnt(1)
; __device__ __forceinline__ unsigned cvt_pk_bf16(float lo, float hi) { unsigned r; asm volatile("v_cvt_pk_bf16_f32 %0, %1, %2" : "=v"(r) : "v"(lo), "v"(hi)); return r; }
;     __device__ __forceinline__ void operator()(const f32x4 (&acc)[2][2][4][2], const Unit& u, int wr, int wc, int fr, int fq) const {
;     ...
;             for (int m = 0; m < 4; ++m) { const int row = row0 + ai * HALF + m * 16; bf16_t* rp = xb + (size_t)row * 2048 + col0; float s = 0.f;
; #pragma unroll
;                 for (int bj = 0; bj < 2; ++bj) { const u32x4 x = *(const u32x4*)(rp + bj * HALF); float v[8];
; #pragma unroll
;                     for (int e = 0; e < 4; ++e) { v[2 * e] = __builtin_bit_cast(float, x[e] << 16) + acc[ai][bj][m][e >> 1][(2 * e) & 3]; v[2 * e + 1] = __builtin_bit_cast(float, x[e] & 0xffff0000u) + acc[ai][bj][m][e >> 1][(2 * e + 1) & 3]; }
; #pragma unroll
;                     for (int e = 0; e < 8; ++e) s += v[e] * v[e];
;                     u32x4 w; w.x = cvt_pk_bf16(v[0], v[1]); w.y = cvt_pk_bf16(v[2], v[3]); w.z = cvt_pk_bf16(v[4], v[5]); w.w = cvt_pk_bf16(v[6], v[7]);
;                     *(u32x4*)(rp + bj * HALF) = w; }
;                 s = sum_x32(sum_x16(s)); asm volatile("" : "+v"(s));
;                 if (fq == 0) atomicAdd(ss + row, s); }
	v_lshlrev_b32_e32 v106, 16, v100
	v_and_b32_e32 v100, 0xffff0000, v100
	v_lshlrev_b32_e32 v107, 16, v101
	v_and_b32_e32 v101, 0xffff0000, v101
	v_lshlrev_b32_e32 v108, 16, v102
	v_and_b32_e32 v102, 0xffff0000, v102
	v_lshlrev_b32_e32 v109, 16, v103
	v_and_b32_e32 v103, 0xffff0000, v103
	v_add_f32_e32 v106, v94, v106
	v_add_f32_e32 v100, v95, v100
	v_add_f32_e32 v107, v96, v107
	v_add_f32_e32 v101, v97, v101
	v_add_f32_e32 v108, v90, v108
	v_add_f32_e32 v102, v91, v102
	v_add_f32_e32 v109, v92, v109
	v_add_f32_e32 v103, v93, v103
	v_cvt_pk_bf16_f32 v90, v106, v100
	v_cvt_pk_bf16_f32 v91, v107, v101
	v_cvt_pk_bf16_f32 v92, v108, v102
	v_cvt_pk_bf16_f32 v93, v109, v103
	s_nop 0
	v_mul_f32_e32 v100, v100, v100
	v_fmac_f32_e32 v100, v106, v106
	v_fmac_f32_e32 v100, v107, v107
	v_fmac_f32_e32 v100, v101, v101
	v_fmac_f32_e32 v100, v108, v108
	v_fmac_f32_e32 v100, v102, v102
	global_store_dwordx4 v[104:105], v[90:93], off
	v_fmac_f32_e32 v100, v109, v109
	v_fmac_f32_e32 v100, v103, v103
	s_waitcnt vmcnt(1)
	v_mov_b32_e32 v94, v186
	v_mov_b32_e32 v95, v187
	v_mov_b32_e32 v96, v188
	v_mov_b32_e32 v97, v189
	v_lshlrev_b32_e32 v90, 16, v94
	v_and_b32_e32 v91, 0xffff0000, v94
	v_add_f32_e32 v86, v86, v90
	v_lshlrev_b32_e32 v92, 16, v95
	v_add_f32_e32 v87, v87, v91
	v_fmac_f32_e32 v100, v86, v86
	v_and_b32_e32 v93, 0xffff0000, v95
	v_add_f32_e32 v88, v88, v92
	v_fmac_f32_e32 v100, v87, v87
	v_lshlrev_b32_e32 v94, 16, v96
	v_add_f32_e32 v89, v89, v93
	v_fmac_f32_e32 v100, v88, v88
	v_and_b32_e32 v95, 0xffff0000, v96
	v_add_f32_e32 v90, v82, v94
	v_fmac_f32_e32 v100, v89, v89
	v_lshlrev_b32_e32 v96, 16, v97
	v_add_f32_e32 v91, v83, v95
	v_fmac_f32_e32 v100, v90, v90
	v_and_b32_e32 v97, 0xffff0000, v97
	v_add_f32_e32 v92, v84, v96
	v_fmac_f32_e32 v100, v91, v91
	v_add_f32_e32 v93, v85, v97
	v_fmac_f32_e32 v100, v92, v92
	v_cvt_pk_bf16_f32 v82, v86, v87
	v_fmac_f32_e32 v100, v93, v93
	v_cvt_pk_bf16_f32 v83, v88, v89
	v_cvt_pk_bf16_f32 v84, v90, v91
	v_cvt_pk_bf16_f32 v85, v92, v93
	global_store_dwordx4 v[104:105], v[82:85], off offset:256
	s_nop 1
	v_mov_b32_e32 v82, v100
	s_nop 1
	v_permlane16_swap_b32_e32 v100, v82
	v_add_f32_e32 v82, v100, v82
	v_mov_b32_e32 v83, v82
	s_nop 1
	v_permlane32_swap_b32_e32 v82, v83
	v_add_f32_e32 v82, v82, v83
	v_mov_b32_e32 v202, v82
	v_or_b32_e32 v82, 48, v148
	v_ashrrev_i32_e32 v83, 31, v82
	v_lshlrev_b64 v[84:85], 12, v[82:83]
	v_lshl_add_u64 v[84:85], s[16:17], 0, v[84:85]
	v_lshl_add_u64 v[88:89], v[146:147], 1, v[84:85]
	global_load_dwordx4 v[84:87], v[88:89], off
	global_load_dwordx4 v[186:189], v[88:89], off offset:256
	s_waitcnt vmcnt(1)
	v_lshlrev_b32_e32 v90, 16, v84
	v_and_b32_e32 v84, 0xffff0000, v84
	v_lshlrev_b32_e32 v91, 16, v85
	v_and_b32_e32 v85, 0xffff0000, v85
	v_lshlrev_b32_e32 v92, 16, v86
	v_and_b32_e32 v86, 0xffff0000, v86
	v_lshlrev_b32_e32 v93, 16, v87
	v_and_b32_e32 v87, 0xffff0000, v87
	v_add_f32_e32 v90, v78, v90
	v_add_f32_e32 v84, v79, v84
	v_add_f32_e32 v91, v80, v91
	v_add_f32_e32 v85, v81, v85
	v_add_f32_e32 v92, v74, v92
	v_add_f32_e32 v86, v75, v86
	v_add_f32_e32 v93, v76, v93
	v_add_f32_e32 v87, v77, v87
	v_cvt_pk_bf16_f32 v74, v90, v84
	v_cvt_pk_bf16_f32 v75, v91, v85
	v_cvt_pk_bf16_f32 v76, v92, v86
	v_cvt_pk_bf16_f32 v77, v93, v87
	s_nop 0
	v_mul_f32_e32 v84, v84, v84
	v_fmac_f32_e32 v84, v90, v90
	v_fmac_f32_e32 v84, v91, v91
	v_fmac_f32_e32 v84, v85, v85
	v_fmac_f32_e32 v84, v92, v92
	v_fmac_f32_e32 v84, v86, v86
	global_store_dwordx4 v[88:89], v[74:77], off
	v_fmac_f32_e32 v84, v93, v93
	v_fmac_f32_e32 v84, v87, v87
	s_waitcnt vmcnt(1)
	v_mov_b32_e32 v78, v186
	v_mov_b32_e32 v79, v187
	v_mov_b32_e32 v80, v188
	v_mov_b32_e32 v81, v189
	v_lshlrev_b32_e32 v74, 16, v78
	v_and_b32_e32 v75, 0xffff0000, v78
	v_add_f32_e32 v70, v70, v74
	v_lshlrev_b32_e32 v76, 16, v79
	v_add_f32_e32 v71, v71, v75
	v_fmac_f32_e32 v84, v70, v70
	v_and_b32_e32 v77, 0xffff0000, v79
	v_add_f32_e32 v72, v72, v76
	v_fmac_f32_e32 v84, v71, v71
	v_lshlrev_b32_e32 v78, 16, v80
	v_add_f32_e32 v73, v73, v77
	v_fmac_f32_e32 v84, v72, v72
	v_and_b32_e32 v79, 0xffff0000, v80
	v_add_f32_e32 v74, v66, v78
	v_fmac_f32_e32 v84, v73, v73
	v_lshlrev_b32_e32 v80, 16, v81
	v_add_f32_e32 v75, v67, v79
	v_fmac_f32_e32 v84, v74, v74
	v_and_b32_e32 v81, 0xffff0000, v81
	v_add_f32_e32 v76, v68, v80
	v_fmac_f32_e32 v84, v75, v75
	v_add_f32_e32 v77, v69, v81
	v_fmac_f32_e32 v84, v76, v76
	v_cvt_pk_bf16_f32 v66, v70, v71
	v_fmac_f32_e32 v84, v77, v77
	v_cvt_pk_bf16_f32 v67, v72, v73
	v_cvt_pk_bf16_f32 v68, v74, v75
	v_cvt_pk_bf16_f32 v69, v76, v77
	global_store_dwordx4 v[88:89], v[66:69], off offset:256
	s_nop 1
	v_mov_b32_e32 v66, v84
	s_nop 1
	v_permlane16_swap_b32_e32 v84, v66
	v_add_f32_e32 v66, v84, v66
	v_mov_b32_e32 v67, v66
	s_nop 1
	v_permlane32_swap_b32_e32 v66, v67
	v_add_f32_e32 v66, v66, v67
	v_mov_b32_e32 v203, v66
	v_add_u32_e32 v66, 0x80, v148
	v_ashrrev_i32_e32 v67, 31, v66
	v_lshlrev_b64 v[68:69], 12, v[66:67]
	v_lshl_add_u64 v[68:69], s[16:17], 0, v[68:69]
	v_lshl_add_u64 v[72:73], v[146:147], 1, v[68:69]
	global_load_dwordx4 v[68:71], v[72:73], off
	global_load_dwordx4 v[186:189], v[72:73], off offset:256
	s_waitcnt vmcnt(1)
	v_lshlrev_b32_e32 v74, 16, v68
	v_and_b32_e32 v68, 0xffff0000, v68
	v_lshlrev_b32_e32 v75, 16, v69
	v_and_b32_e32 v69, 0xffff0000, v69
	v_lshlrev_b32_e32 v76, 16, v70
	v_and_b32_e32 v70, 0xffff0000, v70
	v_lshlrev_b32_e32 v77, 16, v71
	v_and_b32_e32 v71, 0xffff0000, v71
	v_add_f32_e32 v74, v62, v74
	v_add_f32_e32 v68, v63, v68
	v_add_f32_e32 v75, v64, v75
	v_add_f32_e32 v69, v65, v69
	v_add_f32_e32 v76, v58, v76
	v_add_f32_e32 v70, v59, v70
	v_add_f32_e32 v77, v60, v77
	v_add_f32_e32 v71, v61, v71
	v_cvt_pk_bf16_f32 v58, v74, v68
	v_cvt_pk_bf16_f32 v59, v75, v69
	v_cvt_pk_bf16_f32 v60, v76, v70
	v_cvt_pk_bf16_f32 v61, v77, v71
	s_nop 0
	v_mul_f32_e32 v68, v68, v68
	v_fmac_f32_e32 v68, v74, v74
	v_fmac_f32_e32 v68, v75, v75
	v_fmac_f32_e32 v68, v69, v69
	v_fmac_f32_e32 v68, v76, v76
	v_fmac_f32_e32 v68, v70, v70
	global_store_dwordx4 v[72:73], v[58:61], off
	v_fmac_f32_e32 v68, v77, v77
	v_fmac_f32_e32 v68, v71, v71
	s_waitcnt vmcnt(1)
; __device__ __forceinline__ unsigned cvt_pk_bf16(float lo, float hi) { unsigned r; asm volatile("v_cvt_pk_bf16_f32 %0, %1, %2" : "=v"(r) : "v"(lo), "v"(hi)); return r; }
;     __device__ __forceinline__ void operator()(const f32x4 (&acc)[2][2][4][2], const Unit& u, int wr, int wc, int fr, int fq) const {
;     ...
;             for (int m = 0; m < 4; ++m) { const int row = row0 + ai * HALF + m * 16; bf16_t* rp = xb + (size_t)row * 2048 + col0; float s = 0.f;
; #pragma unroll
;                 for (int bj = 0; bj < 2; ++bj) { const u32x4 x = *(const u32x4*)(rp + bj * HALF); float v[8];
; #pragma unroll
;                     for (int e = 0; e < 4; ++e) { v[2 * e] = __builtin_bit_cast(float, x[e] << 16) + acc[ai][bj][m][e >> 1][(2 * e) & 3]; v[2 * e + 1] = __builtin_bit_cast(float, x[e] & 0xffff0000u) + acc[ai][bj][m][e >> 1][(2 * e + 1) & 3]; }
; #pragma unroll
;                     for (int e = 0; e < 8; ++e) s += v[e] * v[e];
;                     u32x4 w; w.x = cvt_pk_bf16(v[0], v[1]); w.y = cvt_pk_bf16(v[2], v[3]); w.z = cvt_pk_bf16(v[4], v[5]); w.w = cvt_pk_bf16(v[6], v[7]);
;                     *(u32x4*)(rp + bj * HALF) = w; }
;                 s = sum_x32(sum_x16(s)); asm volatile("" : "+v"(s));
;                 if (fq == 0) atomicAdd(ss + row, s); }
	v_mov_b32_e32 v62, v186
	v_mov_b32_e32 v63, v187
	v_mov_b32_e32 v64, v188
	v_mov_b32_e32 v65, v189
	v_lshlrev_b32_e32 v58, 16, v62
	v_and_b32_e32 v59, 0xffff0000, v62
	v_add_f32_e32 v54, v54, v58
	v_lshlrev_b32_e32 v60, 16, v63
	v_add_f32_e32 v55, v55, v59
	v_fmac_f32_e32 v68, v54, v54
	v_and_b32_e32 v61, 0xffff0000, v63
	v_add_f32_e32 v56, v56, v60
	v_fmac_f32_e32 v68, v55, v55
	v_lshlrev_b32_e32 v62, 16, v64
	v_add_f32_e32 v57, v57, v61
	v_fmac_f32_e32 v68, v56, v56
	v_and_b32_e32 v63, 0xffff0000, v64
	v_add_f32_e32 v58, v50, v62
	v_fmac_f32_e32 v68, v57, v57
	v_lshlrev_b32_e32 v64, 16, v65
	v_add_f32_e32 v59, v51, v63
	v_fmac_f32_e32 v68, v58, v58
	v_and_b32_e32 v65, 0xffff0000, v65
	v_add_f32_e32 v60, v52, v64
	v_fmac_f32_e32 v68, v59, v59
	v_add_f32_e32 v61, v53, v65
	v_fmac_f32_e32 v68, v60, v60
	v_cvt_pk_bf16_f32 v50, v54, v55
	v_fmac_f32_e32 v68, v61, v61
	v_cvt_pk_bf16_f32 v51, v56, v57
	v_cvt_pk_bf16_f32 v52, v58, v59
	v_cvt_pk_bf16_f32 v53, v60, v61
	global_store_dwordx4 v[72:73], v[50:53], off offset:256
	s_nop 1
	v_mov_b32_e32 v50, v68
	s_nop 1
	v_permlane16_swap_b32_e32 v68, v50
	v_add_f32_e32 v50, v68, v50
	v_mov_b32_e32 v51, v50
	s_nop 1
	v_permlane32_swap_b32_e32 v50, v51
	v_add_f32_e32 v50, v50, v51
	v_mov_b32_e32 v204, v50
	v_add_u32_e32 v50, 0x90, v148
	v_ashrrev_i32_e32 v51, 31, v50
	v_lshlrev_b64 v[52:53], 12, v[50:51]
	v_lshl_add_u64 v[52:53], s[16:17], 0, v[52:53]
	v_lshl_add_u64 v[56:57], v[146:147], 1, v[52:53]
	global_load_dwordx4 v[52:55], v[56:57], off
	global_load_dwordx4 v[186:189], v[56:57], off offset:256
	s_waitcnt vmcnt(1)
	v_lshlrev_b32_e32 v58, 16, v52
	v_and_b32_e32 v52, 0xffff0000, v52
	v_lshlrev_b32_e32 v59, 16, v53
	v_and_b32_e32 v53, 0xffff0000, v53
	v_lshlrev_b32_e32 v60, 16, v54
	v_and_b32_e32 v54, 0xffff0000, v54
	v_lshlrev_b32_e32 v61, 16, v55
	v_and_b32_e32 v55, 0xffff0000, v55
	v_add_f32_e32 v58, v46, v58
	v_add_f32_e32 v52, v47, v52
	v_add_f32_e32 v59, v48, v59
	v_add_f32_e32 v53, v49, v53
	v_add_f32_e32 v60, v42, v60
	v_add_f32_e32 v54, v43, v54
	v_add_f32_e32 v61, v44, v61
	v_add_f32_e32 v55, v45, v55
	v_cvt_pk_bf16_f32 v42, v58, v52
	v_cvt_pk_bf16_f32 v43, v59, v53
	v_cvt_pk_bf16_f32 v44, v60, v54
	v_cvt_pk_bf16_f32 v45, v61, v55
	s_nop 0
	v_mul_f32_e32 v52, v52, v52
	v_fmac_f32_e32 v52, v58, v58
	v_fmac_f32_e32 v52, v59, v59
	v_fmac_f32_e32 v52, v53, v53
	v_fmac_f32_e32 v52, v60, v60
	v_fmac_f32_e32 v52, v54, v54
	global_store_dwordx4 v[56:57], v[42:45], off
	v_fmac_f32_e32 v52, v61, v61
	v_fmac_f32_e32 v52, v55, v55
	s_waitcnt vmcnt(1)
	v_mov_b32_e32 v46, v186
	v_mov_b32_e32 v47, v187
	v_mov_b32_e32 v48, v188
	v_mov_b32_e32 v49, v189
	v_lshlrev_b32_e32 v42, 16, v46
	v_and_b32_e32 v43, 0xffff0000, v46
	v_add_f32_e32 v38, v38, v42
	v_lshlrev_b32_e32 v44, 16, v47
	v_add_f32_e32 v39, v39, v43
	v_fmac_f32_e32 v52, v38, v38
	v_and_b32_e32 v45, 0xffff0000, v47
	v_add_f32_e32 v40, v40, v44
	v_fmac_f32_e32 v52, v39, v39
	v_lshlrev_b32_e32 v46, 16, v48
	v_add_f32_e32 v41, v41, v45
	v_fmac_f32_e32 v52, v40, v40
	v_and_b32_e32 v47, 0xffff0000, v48
	v_add_f32_e32 v42, v34, v46
	v_fmac_f32_e32 v52, v41, v41
	v_lshlrev_b32_e32 v48, 16, v49
	v_add_f32_e32 v43, v35, v47
	v_fmac_f32_e32 v52, v42, v42
	v_and_b32_e32 v49, 0xffff0000, v49
	v_add_f32_e32 v44, v36, v48
	v_fmac_f32_e32 v52, v43, v43
	v_add_f32_e32 v45, v37, v49
	v_fmac_f32_e32 v52, v44, v44
	v_cvt_pk_bf16_f32 v34, v38, v39
	v_fmac_f32_e32 v52, v45, v45
	v_cvt_pk_bf16_f32 v35, v40, v41
	v_cvt_pk_bf16_f32 v36, v42, v43
	v_cvt_pk_bf16_f32 v37, v44, v45
	global_store_dwordx4 v[56:57], v[34:37], off offset:256
	s_nop 1
	v_mov_b32_e32 v34, v52
	s_nop 1
	v_permlane16_swap_b32_e32 v52, v34
	v_add_f32_e32 v34, v52, v34
	v_mov_b32_e32 v35, v34
	s_nop 1
	v_permlane32_swap_b32_e32 v34, v35
	v_add_f32_e32 v34, v34, v35
	v_mov_b32_e32 v205, v34
	v_add_u32_e32 v34, 0xa0, v148
	v_ashrrev_i32_e32 v35, 31, v34
	v_lshlrev_b64 v[36:37], 12, v[34:35]
	v_lshl_add_u64 v[36:37], s[16:17], 0, v[36:37]
	v_lshl_add_u64 v[40:41], v[146:147], 1, v[36:37]
	global_load_dwordx4 v[36:39], v[40:41], off
	global_load_dwordx4 v[186:189], v[40:41], off offset:256
	s_waitcnt vmcnt(1)
	v_lshlrev_b32_e32 v42, 16, v36
	v_and_b32_e32 v36, 0xffff0000, v36
	v_lshlrev_b32_e32 v43, 16, v37
	v_and_b32_e32 v37, 0xffff0000, v37
	v_lshlrev_b32_e32 v44, 16, v38
	v_and_b32_e32 v38, 0xffff0000, v38
	v_lshlrev_b32_e32 v45, 16, v39
	v_and_b32_e32 v39, 0xffff0000, v39
	v_add_f32_e32 v42, v30, v42
	v_add_f32_e32 v36, v31, v36
	v_add_f32_e32 v43, v32, v43
	v_add_f32_e32 v37, v33, v37
	v_add_f32_e32 v44, v26, v44
	v_add_f32_e32 v38, v27, v38
	v_add_f32_e32 v45, v28, v45
	v_add_f32_e32 v39, v29, v39
	v_cvt_pk_bf16_f32 v26, v42, v36
	v_cvt_pk_bf16_f32 v27, v43, v37
	v_cvt_pk_bf16_f32 v28, v44, v38
	v_cvt_pk_bf16_f32 v29, v45, v39
	s_nop 0
	v_mul_f32_e32 v36, v36, v36
	v_fmac_f32_e32 v36, v42, v42
	v_fmac_f32_e32 v36, v43, v43
	v_fmac_f32_e32 v36, v37, v37
	v_fmac_f32_e32 v36, v44, v44
	v_fmac_f32_e32 v36, v38, v38
	global_store_dwordx4 v[40:41], v[26:29], off
	v_fmac_f32_e32 v36, v45, v45
	v_fmac_f32_e32 v36, v39, v39
	s_waitcnt vmcnt(1)
; __device__ __forceinline__ unsigned cvt_pk_bf16(float lo, float hi) { unsigned r; asm volatile("v_cvt_pk_bf16_f32 %0, %1, %2" : "=v"(r) : "v"(lo), "v"(hi)); return r; }
;     __device__ __forceinline__ void operator()(const f32x4 (&acc)[2][2][4][2], const Unit& u, int wr, int wc, int fr, int fq) const {
;     ...
;             for (int m = 0; m < 4; ++m) { const int row = row0 + ai * HALF + m * 16; bf16_t* rp = xb + (size_t)row * 2048 + col0; float s = 0.f;
; #pragma unroll
;                 for (int bj = 0; bj < 2; ++bj) { const u32x4 x = *(const u32x4*)(rp + bj * HALF); float v[8];
; #pragma unroll
;                     for (int e = 0; e < 4; ++e) { v[2 * e] = __builtin_bit_cast(float, x[e] << 16) + acc[ai][bj][m][e >> 1][(2 * e) & 3]; v[2 * e + 1] = __builtin_bit_cast(float, x[e] & 0xffff0000u) + acc[ai][bj][m][e >> 1][(2 * e + 1) & 3]; }
; #pragma unroll
;                     for (int e = 0; e < 8; ++e) s += v[e] * v[e];
;                     u32x4 w; w.x = cvt_pk_bf16(v[0], v[1]); w.y = cvt_pk_bf16(v[2], v[3]); w.z = cvt_pk_bf16(v[4], v[5]); w.w = cvt_pk_bf16(v[6], v[7]);
;                     *(u32x4*)(rp + bj * HALF) = w; }
;                 s = sum_x32(sum_x16(s)); asm volatile("" : "+v"(s));
;                 if (fq == 0) atomicAdd(ss + row, s); }
	v_mov_b32_e32 v30, v186
	v_mov_b32_e32 v31, v187
	v_mov_b32_e32 v32, v188
	v_mov_b32_e32 v33, v189
	v_lshlrev_b32_e32 v26, 16, v30
	v_and_b32_e32 v27, 0xffff0000, v30
	v_add_f32_e32 v22, v22, v26
	v_lshlrev_b32_e32 v28, 16, v31
	v_add_f32_e32 v23, v23, v27
	v_fmac_f32_e32 v36, v22, v22
	v_and_b32_e32 v29, 0xffff0000, v31
	v_add_f32_e32 v24, v24, v28
	v_fmac_f32_e32 v36, v23, v23
	v_lshlrev_b32_e32 v30, 16, v32
	v_add_f32_e32 v25, v25, v29
	v_fmac_f32_e32 v36, v24, v24
	v_and_b32_e32 v31, 0xffff0000, v32
	v_add_f32_e32 v26, v18, v30
	v_fmac_f32_e32 v36, v25, v25
	v_lshlrev_b32_e32 v32, 16, v33
	v_add_f32_e32 v27, v19, v31
	v_fmac_f32_e32 v36, v26, v26
	v_and_b32_e32 v33, 0xffff0000, v33
	v_add_f32_e32 v28, v20, v32
	v_fmac_f32_e32 v36, v27, v27
	v_add_f32_e32 v29, v21, v33
	v_fmac_f32_e32 v36, v28, v28
	v_cvt_pk_bf16_f32 v18, v22, v23
	v_fmac_f32_e32 v36, v29, v29
	v_cvt_pk_bf16_f32 v19, v24, v25
	v_cvt_pk_bf16_f32 v20, v26, v27
	v_cvt_pk_bf16_f32 v21, v28, v29
	global_store_dwordx4 v[40:41], v[18:21], off offset:256
	s_nop 1
	v_mov_b32_e32 v18, v36
	s_nop 1
	v_permlane16_swap_b32_e32 v36, v18
	v_add_f32_e32 v18, v36, v18
	v_mov_b32_e32 v19, v18
	s_nop 1
	v_permlane32_swap_b32_e32 v18, v19
	v_add_f32_e32 v18, v18, v19
	v_mov_b32_e32 v206, v18
	v_add_u32_e32 v18, 0xb0, v148
	v_ashrrev_i32_e32 v19, 31, v18
	v_lshlrev_b64 v[20:21], 12, v[18:19]
	v_lshl_add_u64 v[20:21], s[16:17], 0, v[20:21]
	v_lshl_add_u64 v[24:25], v[146:147], 1, v[20:21]
	global_load_dwordx4 v[20:23], v[24:25], off
	global_load_dwordx4 v[186:189], v[24:25], off offset:256
	s_waitcnt vmcnt(1)
	v_lshlrev_b32_e32 v26, 16, v20
	v_and_b32_e32 v20, 0xffff0000, v20
	v_lshlrev_b32_e32 v27, 16, v21
	v_and_b32_e32 v21, 0xffff0000, v21
	v_lshlrev_b32_e32 v28, 16, v22
	v_and_b32_e32 v22, 0xffff0000, v22
	v_lshlrev_b32_e32 v29, 16, v23
	v_and_b32_e32 v23, 0xffff0000, v23
	v_add_f32_e32 v26, v14, v26
	v_add_f32_e32 v20, v15, v20
	v_add_f32_e32 v27, v16, v27
	v_add_f32_e32 v21, v17, v21
	v_add_f32_e32 v28, v10, v28
	v_add_f32_e32 v22, v11, v22
	v_add_f32_e32 v29, v12, v29
	v_add_f32_e32 v23, v13, v23
	v_cvt_pk_bf16_f32 v10, v26, v20
	v_cvt_pk_bf16_f32 v11, v27, v21
	v_cvt_pk_bf16_f32 v12, v28, v22
	v_cvt_pk_bf16_f32 v13, v29, v23
	s_nop 0
	v_mul_f32_e32 v20, v20, v20
	v_fmac_f32_e32 v20, v26, v26
	v_fmac_f32_e32 v20, v27, v27
	v_fmac_f32_e32 v20, v21, v21
	v_fmac_f32_e32 v20, v28, v28
	v_fmac_f32_e32 v20, v22, v22
	global_store_dwordx4 v[24:25], v[10:13], off
	v_fmac_f32_e32 v20, v29, v29
	v_fmac_f32_e32 v20, v23, v23
	s_waitcnt vmcnt(1)
	v_mov_b32_e32 v14, v186
	v_mov_b32_e32 v15, v187
	v_mov_b32_e32 v16, v188
	v_mov_b32_e32 v17, v189
	v_lshlrev_b32_e32 v10, 16, v14
	v_and_b32_e32 v11, 0xffff0000, v14
	v_add_f32_e32 v6, v6, v10
	v_lshlrev_b32_e32 v12, 16, v15
	v_add_f32_e32 v7, v7, v11
	v_fmac_f32_e32 v20, v6, v6
	v_and_b32_e32 v13, 0xffff0000, v15
	v_add_f32_e32 v8, v8, v12
	v_fmac_f32_e32 v20, v7, v7
	v_lshlrev_b32_e32 v14, 16, v16
	v_add_f32_e32 v9, v9, v13
	v_fmac_f32_e32 v20, v8, v8
	v_and_b32_e32 v15, 0xffff0000, v16
	v_add_f32_e32 v10, v2, v14
	v_fmac_f32_e32 v20, v9, v9
	v_lshlrev_b32_e32 v16, 16, v17
	v_add_f32_e32 v11, v3, v15
	v_fmac_f32_e32 v20, v10, v10
	v_and_b32_e32 v17, 0xffff0000, v17
	v_add_f32_e32 v12, v4, v16
	v_fmac_f32_e32 v20, v11, v11
	v_add_f32_e32 v13, v5, v17
	v_fmac_f32_e32 v20, v12, v12
	v_cvt_pk_bf16_f32 v2, v6, v7
	v_fmac_f32_e32 v20, v13, v13
	v_cvt_pk_bf16_f32 v3, v8, v9
	v_cvt_pk_bf16_f32 v4, v10, v11
	v_cvt_pk_bf16_f32 v5, v12, v13
	global_store_dwordx4 v[24:25], v[2:5], off offset:256
	s_nop 1
	v_mov_b32_e32 v2, v20
	s_nop 1
	v_permlane16_swap_b32_e32 v20, v2
	v_add_f32_e32 v2, v20, v2
	v_mov_b32_e32 v3, v2
	s_nop 1
	v_permlane32_swap_b32_e32 v2, v3
	v_add_f32_e32 v2, v2, v3
	v_mov_b32_e32 v207, v2
	s_and_saveexec_b64 s[24:25], s[4:5]
	global_atomic_add_f32 v[208:209], v200, off
	global_atomic_add_f32 v[208:209], v201, off offset:64
	global_atomic_add_f32 v[208:209], v202, off offset:128
	global_atomic_add_f32 v[208:209], v203, off offset:192
	global_atomic_add_f32 v[208:209], v204, off offset:512
	global_atomic_add_f32 v[208:209], v205, off offset:576
	global_atomic_add_f32 v[208:209], v206, off offset:640
	global_atomic_add_f32 v[208:209], v207, off offset:704
	s_or_b64 exec, exec, s[24:25]
	s_mov_b64 s[24:25], -1
	s_and_b64 vcc, exec, s[6:7]
	s_cbranch_vccz .LBB0_609
	s_andn2_b64 vcc, exec, s[10:11]
	s_cbranch_vccnz .LBB0_608
	s_barrier
	s_branch .LBB0_608
